# grid barrier: the globally last XCD leader bumps every XCD generation word itself (one hand-off hop less for the other XCDs' followers)
# baseline (speedup 1.0000x reference)
; __device__ __forceinline__ unsigned xb_ld(unsigned* p)              { return __hip_atomic_load(p, __ATOMIC_RELAXED, __HIP_MEMORY_SCOPE_AGENT); }
; __device__ __forceinline__ unsigned xb_add(unsigned* p, unsigned v) { return __hip_atomic_fetch_add(p, v, __ATOMIC_RELAXED, __HIP_MEMORY_SCOPE_AGENT); }
; #define XB_SPIN(cond, bar) do { unsigned _sp = 0; while (cond) { __builtin_amdgcn_s_sleep(1); \
;     if ((++_sp & 255u) == 0u) { if (xb_ld(&(bar)[XB_TMO])) break; if (_sp > XB_SPIN_CAP) { atomicAdd(&(bar)[XB_TMO], 1u); break; } } } } while (0)
; __device__ __forceinline__ void grid_barrier(unsigned* bar, unsigned x, volatile LAS unsigned* st, unsigned G, int wv) {
;     ...
;             if (og + 1u == (tg + 1u) * nx) xb_add(&bar[XB_TOPGEN], 1u);
;             else XB_SPIN(xb_ld(&bar[XB_TOPGEN]) == tg, bar);
;             __builtin_amdgcn_fence(__ATOMIC_ACQUIRE, "agent");
;             xb_add(&bar[XB_XGEN(x)], 1u);
.LBB0_173:
	s_or_b64 exec, exec, s[8:9]
	s_and_saveexec_b64 s[8:9], s[12:13]
	s_cbranch_execz .LBB0_175
	v_mov_b32_e32 v2, 1
	global_atomic_add v[0:1], v2, off
	v_mov_b32_e32 v3, 0x2400
	global_atomic_add v3, v2, s[78:79]
	global_atomic_add v3, v2, s[78:79] offset:256
	global_atomic_add v3, v2, s[78:79] offset:512
	global_atomic_add v3, v2, s[78:79] offset:768
	global_atomic_add v3, v2, s[78:79] offset:1024
	global_atomic_add v3, v2, s[78:79] offset:1280
	global_atomic_add v3, v2, s[78:79] offset:1536
	global_atomic_add v3, v2, s[78:79] offset:1792
	global_atomic_add v3, v2, s[78:79] offset:2048
	global_atomic_add v3, v2, s[78:79] offset:2304
	global_atomic_add v3, v2, s[78:79] offset:2560
	global_atomic_add v3, v2, s[78:79] offset:2816
	global_atomic_add v3, v2, s[78:79] offset:3072
	global_atomic_add v3, v2, s[78:79] offset:3328
	global_atomic_add v3, v2, s[78:79] offset:3584
	global_atomic_add v3, v2, s[78:79] offset:3840
.LBB0_175:
	s_or_b64 exec, exec, s[8:9]
	s_mov_b64 s[8:9], exec
	v_mbcnt_lo_u32_b32 v0, s8, 0
	v_mbcnt_hi_u32_b32 v0, s9, v0
	v_cmp_eq_u32_e32 vcc, 0, v0
	s_waitcnt vmcnt(0)
	s_and_saveexec_b64 s[10:11], vcc
	s_cbranch_execz .LBB0_177
	s_bcnt1_i32_b64 s8, s[8:9]
	v_mov_b32_e32 v0, 0x2000
	v_mov_b32_e32 v1, s8
	s_nop 0

; __device__ __forceinline__ unsigned xb_ld(unsigned* p)              { return __hip_atomic_load(p, __ATOMIC_RELAXED, __HIP_MEMORY_SCOPE_AGENT); }
; __device__ __forceinline__ unsigned xb_add(unsigned* p, unsigned v) { return __hip_atomic_fetch_add(p, v, __ATOMIC_RELAXED, __HIP_MEMORY_SCOPE_AGENT); }
; #define XB_SPIN(cond, bar) do { unsigned _sp = 0; while (cond) { __builtin_amdgcn_s_sleep(1); \
;     if ((++_sp & 255u) == 0u) { if (xb_ld(&(bar)[XB_TMO])) break; if (_sp > XB_SPIN_CAP) { atomicAdd(&(bar)[XB_TMO], 1u); break; } } } } while (0)
; __device__ __forceinline__ void grid_barrier(unsigned* bar, unsigned x, volatile LAS unsigned* st, unsigned G, int wv) {
;     ...
;             if (og + 1u == (tg + 1u) * nx) xb_add(&bar[XB_TOPGEN], 1u);
;             else XB_SPIN(xb_ld(&bar[XB_TOPGEN]) == tg, bar);
;             __builtin_amdgcn_fence(__ATOMIC_ACQUIRE, "agent");
;             xb_add(&bar[XB_XGEN(x)], 1u);
.LBB0_453:
	s_or_b64 exec, exec, s[6:7]
	s_and_saveexec_b64 s[6:7], s[10:11]
	s_cbranch_execz .LBB0_455
	v_mov_b32_e32 v2, 1
	global_atomic_add v[0:1], v2, off
	v_mov_b32_e32 v3, 0x2400
	global_atomic_add v3, v2, s[78:79]
	global_atomic_add v3, v2, s[78:79] offset:256
	global_atomic_add v3, v2, s[78:79] offset:512
	global_atomic_add v3, v2, s[78:79] offset:768
	global_atomic_add v3, v2, s[78:79] offset:1024
	global_atomic_add v3, v2, s[78:79] offset:1280
	global_atomic_add v3, v2, s[78:79] offset:1536
	global_atomic_add v3, v2, s[78:79] offset:1792
	global_atomic_add v3, v2, s[78:79] offset:2048
	global_atomic_add v3, v2, s[78:79] offset:2304
	global_atomic_add v3, v2, s[78:79] offset:2560
	global_atomic_add v3, v2, s[78:79] offset:2816
	global_atomic_add v3, v2, s[78:79] offset:3072
	global_atomic_add v3, v2, s[78:79] offset:3328
	global_atomic_add v3, v2, s[78:79] offset:3584
	global_atomic_add v3, v2, s[78:79] offset:3840
.LBB0_455:
	s_or_b64 exec, exec, s[6:7]
	s_mov_b64 s[6:7], exec
	v_mbcnt_lo_u32_b32 v0, s6, 0
	v_mbcnt_hi_u32_b32 v0, s7, v0
	v_cmp_eq_u32_e32 vcc, 0, v0
	s_waitcnt vmcnt(0)
	s_and_saveexec_b64 s[8:9], vcc
	s_cbranch_execz .LBB0_457
	s_bcnt1_i32_b64 s6, s[6:7]
	v_mov_b32_e32 v0, 0x2000
	v_mov_b32_e32 v1, s6
	s_nop 0
